# gMLP unit: gain/Ws/u loads batched instead of one round trip each (on top of norm+prologue edits)
# baseline (speedup 1.0000x reference)
; __device__ __forceinline__ unsigned cvt_pk_bf16(float lo, float hi) { unsigned r; asm volatile("v_cvt_pk_bf16_f32 %0, %1, %2" : "=v"(r) : "v"(lo), "v"(hi)); return r; }
; __device__ __forceinline__ void gmlp_unit(LAS unsigned char* lds, const bf16_t* __restrict__ UV, const bf16_t* __restrict__ Wsb  , const float* __restrict__ gain  ,
;                                           const float* __restrict__ bs  , int r0, int h, bf16_t* __restrict__ O, int tid) {
;     ...
;     const int lane = tid & 63, w = tid >> 6, fr = lane & 15, fq = lane >> 4;
;     {
;         const int q = tid >> 2, part = tid & 3;
;         const bf16_t* src = UV + (size_t)(r0 + q) * 512 + 256 + 64 * h + 16 * part;
;         const u32x4 a0 = *(const u32x4*)src, a1 = *(const u32x4*)(src + 8);
;         float v[16];
; #pragma unroll
;         for (int i = 0; i < 4; ++i) { v[2 * i] = __uint_as_float(a0[i] << 16); v[2 * i + 1] = __uint_as_float(a0[i] & 0xffff0000u); v[8 + 2 * i] = __uint_as_float(a1[i] << 16); v[8 + 2 * i + 1] = __uint_as_float(a1[i] & 0xffff0000u); }
;         float ss = 0.f;
; #pragma unroll
;         for (int i = 0; i < 16; ++i) ss += v[i] * v[i];
;         ss += __shfl_xor(ss, 1); ss += __shfl_xor(ss, 2);
;         const float rstd = rsqrtf(ss * (1.0f / 64.0f) + EPSV);
; #pragma unroll
;         for (int i = 0; i < 16; ++i) { const int c = 16 * part + i; vT[c * VP + q] = (bf16_t)(cvt_pk_bf16(v[i] * rstd * gain[c], 0.f) & 0xffffu); }
; __device__ __forceinline__ void mix_phase(const Args& a, LAS unsigned char* lds, int l, int tid_in, int G) {
;     ...
;             const int v = u - e3, ch = v >> 2, h = v & 3;
;             gmlp_unit(lds, UV, (const bf16_t*)(ws + WS_WS) + (size_t)(l * 4 + h) * 128 * 128, a.in[I_VGAIN] + (l * 4 + h) * 64, a.in[I_BS] + (l * 4 + h) * 128, ch * 128, h, O, tid);
.LBB0_106:
	v_mov_b32_e32 v176, v158
	s_mov_b64 s[0:1], -1
	v_ashrrev_i32_e32 v174, 2, v176
	v_bfe_u32 v177, v176, 4, 2
	s_cmp_ge_i32 s22, s18
	v_and_b32_e32 v173, 15, v176
	v_bfi_b32 v160, -16, v174, v176
	v_lshlrev_b32_e32 v162, 4, v177
	s_cbranch_scc0 .LBB0_108
	s_and_b32 s14, s22, 3
	s_or_b32 s0, s14, s19
	s_ashr_i32 s1, s0, 31
	s_sub_i32 s3, s22, s18
	s_lshl_b64 s[8:9], s[0:1], 15
	v_readlane_b32 s10, v252, 16
	v_readlane_b32 s11, v252, 17
	s_add_u32 s8, s10, s8
	s_addc_u32 s9, s11, s9
	s_lshl_b32 s10, s0, 6
	s_ashr_i32 s11, s10, 31
	v_readlane_b32 s40, v254, 11
	s_lshl_b64 s[10:11], s[10:11], 2
	v_readlane_b32 s50, v254, 21
	v_readlane_b32 s51, v254, 22
	s_add_u32 s10, s50, s10
	s_addc_u32 s11, s51, s11
	s_lshl_b32 s0, s0, 7
	s_ashr_i32 s1, s0, 31
	v_readlane_b32 s54, v254, 25
	s_lshl_b64 s[0:1], s[0:1], 2
	v_readlane_b32 s55, v254, 26
	s_add_u32 s0, s54, s0
	s_addc_u32 s1, s55, s1
	s_lshl_b32 s3, s3, 5
	s_and_b32 s3, s3, 0x7fffff80
	s_waitcnt lgkmcnt(0)
	v_add_u32_e32 v2, s3, v174
	v_ashrrev_i32_e32 v3, 31, v2
	v_readlane_b32 s20, v252, 41
	v_lshlrev_b64 v[2:3], 10, v[2:3]
	v_readlane_b32 s21, v252, 42
	v_lshlrev_b32_e32 v0, 4, v176
	s_lshl_b32 s16, s14, 7
	v_lshl_add_u64 v[2:3], s[20:21], 0, v[2:3]
	s_waitcnt vmcnt(0)
	v_and_b32_e32 v17, 48, v0
	v_lshl_add_u64 v[2:3], v[2:3], 0, s[16:17]
	v_lshlrev_b32_e32 v0, 1, v17
	v_lshl_add_u64 v[2:3], v[2:3], 0, v[0:1]
	global_load_dwordx4 v[20:23], v[2:3], off offset:528
	s_nop 0
	global_load_dwordx4 v[2:5], v[2:3], off offset:512
	v_xor_b32_e32 v19, 1, v191
	v_ashrrev_i32_e32 v161, 31, v160
	v_mov_b32_e32 v163, v1
	v_readlane_b32 s41, v254, 12
	v_readlane_b32 s42, v254, 13
	v_readlane_b32 s43, v254, 14
	v_readlane_b32 s44, v254, 15
	v_readlane_b32 s45, v254, 16
	v_readlane_b32 s46, v254, 17
	v_readlane_b32 s47, v254, 18
	v_readlane_b32 s48, v254, 19
	v_readlane_b32 s49, v254, 20
	v_readlane_b32 s52, v254, 23
	v_readlane_b32 s53, v254, 24
	s_waitcnt vmcnt(1)
	v_and_b32_e32 v8, 0xffff0000, v20
	s_waitcnt vmcnt(0)
	v_and_b32_e32 v18, 0xffff0000, v2
	v_lshlrev_b32_e32 v16, 16, v2
	v_mul_f32_e32 v0, v18, v18
	v_lshlrev_b32_e32 v15, 16, v3
	v_fmac_f32_e32 v0, v16, v16
	v_and_b32_e32 v14, 0xffff0000, v3
	v_fmac_f32_e32 v0, v15, v15
	v_lshlrev_b32_e32 v13, 16, v4
	v_fmac_f32_e32 v0, v14, v14
	v_and_b32_e32 v12, 0xffff0000, v4
	v_fmac_f32_e32 v0, v13, v13
	v_lshlrev_b32_e32 v11, 16, v5
	v_fmac_f32_e32 v0, v12, v12
	v_and_b32_e32 v10, 0xffff0000, v5
	v_fmac_f32_e32 v0, v11, v11
	v_lshlrev_b32_e32 v9, 16, v20
	v_fmac_f32_e32 v0, v10, v10
	v_pk_mul_f32 v[2:3], v[8:9], v[8:9]
	v_and_b32_e32 v6, 0xffff0000, v21
	v_add_f32_e32 v0, v3, v0
	v_lshlrev_b32_e32 v7, 16, v21
	v_add_f32_e32 v0, v2, v0
	v_pk_mul_f32 v[2:3], v[6:7], v[6:7]
	v_and_b32_e32 v4, 0xffff0000, v22
	v_add_f32_e32 v0, v3, v0
	v_lshlrev_b32_e32 v5, 16, v22
	v_add_f32_e32 v0, v2, v0
	v_pk_mul_f32 v[2:3], v[4:5], v[4:5]
	s_nop 0
	v_add_f32_e32 v0, v3, v0
	v_add_f32_e32 v0, v2, v0
	v_and_b32_e32 v2, 0xffff0000, v23
	v_lshlrev_b32_e32 v3, 16, v23
	v_pk_mul_f32 v[20:21], v[2:3], v[2:3]
	s_nop 0
	v_add_f32_e32 v0, v21, v0
	v_add_f32_e32 v0, v20, v0
	v_and_b32_e32 v20, 64, v191
	v_add_u32_e32 v20, 64, v20
	v_cmp_lt_i32_e32 vcc, v19, v20
	s_nop 1
	v_cndmask_b32_e32 v19, v191, v19, vcc
	v_lshlrev_b32_e32 v19, 2, v19
	ds_bpermute_b32 v19, v19, v0
	s_waitcnt lgkmcnt(0)
	v_add_f32_e32 v0, v0, v19
	v_xor_b32_e32 v19, 2, v191
	v_cmp_lt_i32_e32 vcc, v19, v20
	s_nop 1
	v_cndmask_b32_e32 v19, v191, v19, vcc
	v_lshlrev_b32_e32 v19, 2, v19
	ds_bpermute_b32 v19, v19, v0
	s_waitcnt lgkmcnt(0)
	v_add_f32_e32 v0, v0, v19
	v_fmamk_f32 v0, v0, 0x3c800000, v185
	v_cmp_gt_f32_e32 vcc, s33, v0
	v_mul_f32_e32 v19, 0x4b800000, v0
	s_nop 0
	v_cndmask_b32_e32 v0, v0, v19, vcc
	v_rsq_f32_e32 v0, v0
	s_nop 0
	v_mul_f32_e32 v19, 0x45800000, v0
	v_cndmask_b32_e32 v0, v0, v19, vcc
	v_mul_f32_e32 v20, v0, v16
	v_lshlrev_b32_e32 v16, 2, v17
	global_load_dword v235, v16, s[10:11]
	global_load_dword v236, v16, s[10:11] offset:4
	global_load_dword v237, v16, s[10:11] offset:8
	global_load_dword v238, v16, s[10:11] offset:12
	global_load_dword v239, v16, s[10:11] offset:16
	global_load_dword v240, v16, s[10:11] offset:20
	global_load_dword v241, v16, s[10:11] offset:24
	global_load_dword v242, v16, s[10:11] offset:28
	global_load_dword v243, v16, s[10:11] offset:32
	global_load_dword v244, v16, s[10:11] offset:36
	global_load_dword v245, v16, s[10:11] offset:40
	global_load_dword v246, v16, s[10:11] offset:44
	global_load_dword v247, v16, s[10:11] offset:48
	global_load_dword v248, v16, s[10:11] offset:52
	global_load_dword v249, v16, s[10:11] offset:56
	global_load_dword v250, v16, s[10:11] offset:60
	v_lshlrev_b32_e32 v19, 1, v174
	v_mul_u32_u24_e32 v17, 0x110, v17
	v_add3_u32 v17, 0, v19, v17
	v_mul_f32_e32 v18, v0, v18
	v_mul_f32_e32 v15, v0, v15
	v_mul_f32_e32 v14, v0, v14
	v_mul_f32_e32 v13, v0, v13
	v_mul_f32_e32 v12, v0, v12
	v_mul_f32_e32 v11, v0, v11
	v_mul_f32_e32 v10, v0, v10
	v_mul_f32_e32 v9, v0, v9
	v_mul_f32_e32 v8, v0, v8
	v_mul_f32_e32 v7, v0, v7
	v_mul_f32_e32 v6, v0, v6
	v_mul_f32_e32 v5, v0, v5
	v_mul_f32_e32 v4, v0, v4
	v_mul_f32_e32 v3, v0, v3
	v_mul_f32_e32 v0, v0, v2
	s_waitcnt vmcnt(0)
; __device__ __forceinline__ unsigned cvt_pk_bf16(float lo, float hi) { unsigned r; asm volatile("v_cvt_pk_bf16_f32 %0, %1, %2" : "=v"(r) : "v"(lo), "v"(hi)); return r; }
; __device__ __forceinline__ void gmlp_unit(LAS unsigned char* lds, const bf16_t* __restrict__ UV, const bf16_t* __restrict__ Wsb  , const float* __restrict__ gain  ,
;                                           const float* __restrict__ bs  , int r0, int h, bf16_t* __restrict__ O, int tid) {
;     ...
;         for (int i = 0; i < 16; ++i) { const int c = 16 * part + i; vT[c * VP + q] = (bf16_t)(cvt_pk_bf16(v[i] * rstd * gain[c], 0.f) & 0xffffu); }
;     }
;     __syncthreads();
;     f32x4 acc[4];
; #pragma unroll
;     for (int nt = 0; nt < 4; ++nt) acc[nt] = (f32x4){0.f, 0.f, 0.f, 0.f};
; #pragma unroll
;     for (int ks = 0; ks < 4; ++ks) {
;         const bf16x8 wf = *(const bf16x8*)(Wsb + (size_t)(16 * w + fr) * 128 + 32 * ks + 8 * fq);
	v_mul_f32_e32 v20, v235, v20
	v_cvt_pk_bf16_f32 v20, v20, v1
	ds_write_b16 v17, v20
	v_mul_f32_e32 v18, v236, v18
	v_cvt_pk_bf16_f32 v18, v18, v1
	ds_write_b16 v17, v18 offset:272
	v_mul_f32_e32 v15, v237, v15
	v_cvt_pk_bf16_f32 v15, v15, v1
	ds_write_b16 v17, v15 offset:544
	v_mul_f32_e32 v14, v238, v14
	v_cvt_pk_bf16_f32 v14, v14, v1
	ds_write_b16 v17, v14 offset:816
	v_mul_f32_e32 v13, v239, v13
	v_cvt_pk_bf16_f32 v13, v13, v1
	ds_write_b16 v17, v13 offset:1088
	v_mul_f32_e32 v12, v240, v12
	v_cvt_pk_bf16_f32 v12, v12, v1
	ds_write_b16 v17, v12 offset:1360
	v_mul_f32_e32 v11, v241, v11
	v_cvt_pk_bf16_f32 v11, v11, v1
	ds_write_b16 v17, v11 offset:1632
	v_mul_f32_e32 v10, v242, v10
	v_cvt_pk_bf16_f32 v10, v10, v1
	ds_write_b16 v17, v10 offset:1904
	v_mul_f32_e32 v9, v9, v243
	v_cvt_pk_bf16_f32 v9, v9, v1
	ds_write_b16 v17, v9 offset:2176
	v_mul_f32_e32 v8, v8, v244
	v_cvt_pk_bf16_f32 v8, v8, v1
	ds_write_b16 v17, v8 offset:2448
	v_mul_f32_e32 v7, v7, v245
	v_cvt_pk_bf16_f32 v7, v7, v1
	ds_write_b16 v17, v7 offset:2720
	v_mul_f32_e32 v6, v6, v246
	v_cvt_pk_bf16_f32 v6, v6, v1
	ds_write_b16 v17, v6 offset:2992
	v_mul_f32_e32 v5, v5, v247
	v_cvt_pk_bf16_f32 v5, v5, v1
	ds_write_b16 v17, v5 offset:3264
	v_mul_u32_u24_e32 v6, 0x110, v173
	v_add3_u32 v28, 0, v162, v6
	v_mul_f32_e32 v4, v4, v248
	v_cvt_pk_bf16_f32 v4, v4, v1
	ds_write_b16 v17, v4 offset:3536
	v_mul_f32_e32 v3, v3, v249
	v_cvt_pk_bf16_f32 v3, v3, v1
	ds_write_b16 v17, v3 offset:3808
	v_mul_f32_e32 v0, v0, v250
	v_lshlrev_b64 v[2:3], 8, v[160:161]
	v_lshl_add_u64 v[2:3], s[8:9], 0, v[2:3]
	v_lshl_add_u64 v[26:27], v[2:3], 0, v[162:163]
	global_load_dwordx4 v[236:239], v[26:27], off
	global_load_dwordx4 v[240:243], v[26:27], off offset:64
	global_load_dwordx4 v[244:247], v[26:27], off offset:128
	global_load_dwordx4 v[248:251], v[26:27], off offset:192
	v_cvt_pk_bf16_f32 v0, v0, v1
	ds_write_b16 v17, v0 offset:4080
	s_waitcnt lgkmcnt(0)
	s_barrier
; #define LAS __attribute__((address_space(3)))
; __device__ __forceinline__ unsigned cvt_pk_bf16(float lo, float hi) { unsigned r; asm volatile("v_cvt_pk_bf16_f32 %0, %1, %2" : "=v"(r) : "v"(lo), "v"(hi)); return r; }
; __device__ __forceinline__ void gmlp_unit(LAS unsigned char* lds, const bf16_t* __restrict__ UV, const bf16_t* __restrict__ Wsb  , const float* __restrict__ gain  ,
;                                           const float* __restrict__ bs  , int r0, int h, bf16_t* __restrict__ O, int tid) {
;     ...
;     f32x4 acc[4];
; #pragma unroll
;     for (int nt = 0; nt < 4; ++nt) acc[nt] = (f32x4){0.f, 0.f, 0.f, 0.f};
; #pragma unroll
;     for (int ks = 0; ks < 4; ++ks) {
;         const bf16x8 wf = *(const bf16x8*)(Wsb + (size_t)(16 * w + fr) * 128 + 32 * ks + 8 * fq);
; #pragma unroll
;         for (int nt = 0; nt < 4; ++nt) { const bf16x8 vf = *(const LAS bf16x8*)(vT + (16 * nt + fr) * VP + 32 * ks + 8 * fq);
;             acc[nt] = __builtin_amdgcn_mfma_f32_16x16x32_bf16(vf, wf, acc[nt], 0, 0, 0); }
;     }
;     const int p = 16 * w + fr; const float bias = bs[p];
;     const bf16_t* up = UV + (size_t)(r0 + p) * 512 + 64 * h + 4 * fq;
;     bf16_t* op = O + (size_t)(r0 + p) * DM + 64 * h + 4 * fq;
; #pragma unroll
;     for (int nt = 0; nt < 4; ++nt) {
;         const u32x2 uu = *(const u32x2*)(up + 16 * nt);
;         const float u0 = __uint_as_float(uu.x << 16), u1 = __uint_as_float(uu.x & 0xffff0000u), u2 = __uint_as_float(uu.y << 16), u3 = __uint_as_float(uu.y & 0xffff0000u);
;         *(u32x2*)(op + 16 * nt) = (u32x2){cvt_pk_bf16(u0 * (acc[nt][0] + bias), u1 * (acc[nt][1] + bias)), cvt_pk_bf16(u2 * (acc[nt][2] + bias), u3 * (acc[nt][3] + bias))};
;     }
;     __syncthreads();
	s_waitcnt vmcnt(3)
	v_mov_b64_e32 v[2:3], v[236:237]
	v_mov_b64_e32 v[4:5], v[238:239]
	ds_read_b128 v[6:9], v28
	ds_read_b128 v[22:25], v28 offset:64
	ds_read_b128 v[10:13], v28 offset:4352
	ds_read_b128 v[14:17], v28 offset:8704
	ds_read_b128 v[18:21], v28 offset:13056
	v_lshlrev_b32_e32 v0, 3, v177
	s_waitcnt lgkmcnt(4)
	v_mfma_f32_16x16x32_bf16 v[6:9], v[6:9], v[2:5], 0
	s_waitcnt lgkmcnt(2)
	v_mfma_f32_16x16x32_bf16 v[10:13], v[10:13], v[2:5], 0
	s_waitcnt lgkmcnt(1)
	v_mfma_f32_16x16x32_bf16 v[14:17], v[14:17], v[2:5], 0
	s_waitcnt lgkmcnt(0)
	v_mfma_f32_16x16x32_bf16 v[2:5], v[18:21], v[2:5], 0
	s_waitcnt vmcnt(2)
	v_mov_b64_e32 v[18:19], v[240:241]
	v_mov_b64_e32 v[20:21], v[242:243]
	s_nop 1
	v_mfma_f32_16x16x32_bf16 v[6:9], v[22:25], v[18:21], v[6:9]
	ds_read_b128 v[22:25], v28 offset:4416
	s_waitcnt lgkmcnt(0)
	v_mfma_f32_16x16x32_bf16 v[10:13], v[22:25], v[18:21], v[10:13]
	ds_read_b128 v[22:25], v28 offset:8768
	s_waitcnt lgkmcnt(0)
	v_mfma_f32_16x16x32_bf16 v[14:17], v[22:25], v[18:21], v[14:17]
	ds_read_b128 v[22:25], v28 offset:13120
	s_waitcnt lgkmcnt(0)
	v_mfma_f32_16x16x32_bf16 v[2:5], v[22:25], v[18:21], v[2:5]
	s_waitcnt vmcnt(1)
	v_mov_b64_e32 v[18:19], v[244:245]
	v_mov_b64_e32 v[20:21], v[246:247]
	s_nop 1
	ds_read_b128 v[22:25], v28 offset:128
	s_waitcnt lgkmcnt(0)
	v_mfma_f32_16x16x32_bf16 v[6:9], v[22:25], v[18:21], v[6:9]
	ds_read_b128 v[22:25], v28 offset:4480
	s_waitcnt lgkmcnt(0)
	v_mfma_f32_16x16x32_bf16 v[10:13], v[22:25], v[18:21], v[10:13]
	ds_read_b128 v[22:25], v28 offset:8832
	s_waitcnt lgkmcnt(0)
	v_mfma_f32_16x16x32_bf16 v[22:25], v[22:25], v[18:21], v[14:17]
	s_nop 2
	ds_read_b128 v[14:17], v28 offset:13184
	s_waitcnt lgkmcnt(0)
	v_mfma_f32_16x16x32_bf16 v[2:5], v[14:17], v[18:21], v[2:5]
	s_waitcnt vmcnt(0)
	v_mov_b64_e32 v[18:19], v[248:249]
	v_mov_b64_e32 v[20:21], v[250:251]
	s_nop 1
	ds_read_b128 v[14:17], v28 offset:192
	s_waitcnt lgkmcnt(0)
	v_mfma_f32_16x16x32_bf16 v[14:17], v[14:17], v[18:21], v[6:9]
	s_nop 2
	ds_read_b128 v[6:9], v28 offset:4544
	s_waitcnt lgkmcnt(0)
	v_mfma_f32_16x16x32_bf16 v[10:13], v[6:9], v[18:21], v[10:13]
	ds_read_b128 v[6:9], v28 offset:8896
	s_waitcnt lgkmcnt(0)
	v_mfma_f32_16x16x32_bf16 v[6:9], v[6:9], v[18:21], v[22:25]
	s_nop 2
	ds_read_b128 v[22:25], v28 offset:13248
	s_waitcnt lgkmcnt(0)
	v_mfma_f32_16x16x32_bf16 v[2:5], v[22:25], v[18:21], v[2:5]
	v_lshl_add_u64 v[18:19], v[160:161], 2, s[0:1]
	global_load_dword v22, v[18:19], off
	v_add_u32_e32 v18, s3, v160
	v_ashrrev_i32_e32 v19, 31, v18
	v_lshlrev_b64 v[20:21], 10, v[18:19]
	v_lshl_add_u64 v[20:21], s[20:21], 0, v[20:21]
	v_lshl_add_u64 v[20:21], v[20:21], 0, s[16:17]
	v_lshl_add_u64 v[20:21], v[20:21], 0, v[0:1]
	global_load_dwordx2 v[24:25], v[20:21], off
	global_load_dwordx2 v[236:237], v[20:21], off offset:32
	global_load_dwordx2 v[238:239], v[20:21], off offset:64
	global_load_dwordx2 v[240:241], v[20:21], off offset:96
	v_readlane_b32 s0, v252, 55
	v_lshlrev_b64 v[18:19], 11, v[18:19]
	v_readlane_b32 s1, v252, 56
	s_waitcnt vmcnt(4)
	v_add_f32_e32 v14, v14, v22
	v_lshl_add_u64 v[18:19], s[0:1], 0, v[18:19]
	v_lshl_add_u64 v[18:19], v[18:19], 0, s[16:17]
	v_lshl_add_u64 v[18:19], v[18:19], 0, v[0:1]
	v_add_f32_e32 v10, v10, v22
	v_add_f32_e32 v6, v6, v22
	v_add_f32_e32 v2, v22, v2
	s_waitcnt vmcnt(3)
	v_lshlrev_b32_e32 v0, 16, v24
	v_and_b32_e32 v23, 0xffff0000, v24
	v_mul_f32_e32 v0, v14, v0
	v_add_f32_e32 v14, v15, v22
	v_lshlrev_b32_e32 v24, 16, v25
	v_and_b32_e32 v25, 0xffff0000, v25
	v_mul_f32_e32 v14, v14, v23
	v_add_f32_e32 v15, v17, v22
	v_cvt_pk_bf16_f32 v14, v0, v14
	v_add_f32_e32 v0, v16, v22
	v_mul_f32_e32 v15, v15, v25
	v_mul_f32_e32 v0, v0, v24
	v_cvt_pk_bf16_f32 v15, v0, v15
	global_store_dwordx2 v[18:19], v[14:15], off
	s_nop 1
	s_waitcnt vmcnt(3)
	v_mov_b64_e32 v[14:15], v[236:237]
	s_mov_b64 s[0:1], 0
	v_lshlrev_b32_e32 v0, 16, v14
	v_and_b32_e32 v14, 0xffff0000, v14
	v_mul_f32_e32 v0, v10, v0
	v_add_f32_e32 v10, v11, v22
	v_lshlrev_b32_e32 v16, 16, v15
	v_and_b32_e32 v15, 0xffff0000, v15
	v_mul_f32_e32 v10, v10, v14
	v_add_f32_e32 v11, v13, v22
	v_cvt_pk_bf16_f32 v10, v0, v10
	v_add_f32_e32 v0, v12, v22
	v_mul_f32_e32 v11, v11, v15
	v_mul_f32_e32 v0, v0, v16
	v_cvt_pk_bf16_f32 v11, v0, v11
	global_store_dwordx2 v[18:19], v[10:11], off offset:32
	s_nop 1
	s_waitcnt vmcnt(3)
	v_mov_b64_e32 v[10:11], v[238:239]
	v_lshlrev_b32_e32 v0, 16, v10
	v_and_b32_e32 v10, 0xffff0000, v10
	v_mul_f32_e32 v0, v6, v0
	v_add_f32_e32 v6, v7, v22
	v_lshlrev_b32_e32 v12, 16, v11
	v_and_b32_e32 v11, 0xffff0000, v11
	v_mul_f32_e32 v6, v6, v10
	v_add_f32_e32 v7, v9, v22
	v_cvt_pk_bf16_f32 v6, v0, v6
	v_add_f32_e32 v0, v8, v22
	v_mul_f32_e32 v7, v7, v11
	v_mul_f32_e32 v0, v0, v12
	v_cvt_pk_bf16_f32 v7, v0, v7
	global_store_dwordx2 v[18:19], v[6:7], off offset:64
	s_nop 1
	s_waitcnt vmcnt(3)
	v_mov_b64_e32 v[6:7], v[240:241]
	v_lshlrev_b32_e32 v0, 16, v6
	v_and_b32_e32 v6, 0xffff0000, v6
	v_mul_f32_e32 v0, v2, v0
	v_add_f32_e32 v2, v22, v3
	v_lshlrev_b32_e32 v8, 16, v7
	v_and_b32_e32 v7, 0xffff0000, v7
	v_mul_f32_e32 v2, v2, v6
	v_add_f32_e32 v3, v22, v5
	v_cvt_pk_bf16_f32 v2, v0, v2
	v_add_f32_e32 v0, v22, v4
	v_mul_f32_e32 v3, v3, v7
	v_mul_f32_e32 v0, v0, v8
	v_cvt_pk_bf16_f32 v3, v0, v3
	global_store_dwordx2 v[18:19], v[2:3], off offset:96
	s_barrier
